# static priority raise (waves 4-7) with the pre-MFMA setprio toggles deleted, post-MFMA ones kept as s_nop 0
# speedup vs baseline: 1.0071x; 1.0003x over previous
; DI unsigned pk2(float a, float b) { f32x2 v = {a, b}; bf16x2_t r = __builtin_convertvector(v, bf16x2_t); return __builtin_bit_cast(unsigned, r); }
; DI f32x4 mfma16(bf16x8 a, bf16x8 b, f32x4 c) { return __builtin_amdgcn_mfma_f32_16x16x32_bf16(a, b, c, 0, 0, 0); }
; #define SB0 __builtin_amdgcn_sched_barrier(0)
; DI void diff_PV(f32x4 (&o0)[8], f32x4 (&o1)[8], const char* Vb, const bf16x8 (&p0)[2], const bf16x8 (&p1)[2], bf16x8 (&v0)[4], bf16x8 (&v1)[4], int lr, int quad) {
;   bf16x8 v2[4], v3[4];
;   SB0;
;   ldv4(v2, Vb, 2, lr, quad);
;   __builtin_amdgcn_s_setprio(1);
; #pragma unroll
;   for (int i = 0; i < 4; ++i) { o0[i] = mfma16(v0[i], p0[0], o0[i]); o1[i] = mfma16(v0[i], p1[0], o1[i]); }
;   __builtin_amdgcn_s_setprio(0);
;   SB0;
;   ldv4(v3, Vb, 3, lr, quad);
;   __builtin_amdgcn_s_setprio(1);
; #pragma unroll
;   for (int i = 0; i < 4; ++i) { o0[4 + i] = mfma16(v1[i], p0[0], o0[4 + i]); o1[4 + i] = mfma16(v1[i], p1[0], o1[4 + i]); }
;   __builtin_amdgcn_s_setprio(0);
;   SB0;
;   __builtin_amdgcn_s_setprio(1);
; #pragma unroll
;   for (int i = 0; i < 4; ++i) { o0[i] = mfma16(v2[i], p0[1], o0[i]); o1[i] = mfma16(v2[i], p1[1], o1[i]); }
;   __builtin_amdgcn_s_setprio(0);
;   __builtin_amdgcn_s_setprio(1);
; #pragma unroll
;   for (int i = 0; i < 4; ++i) { o0[4 + i] = mfma16(v3[i], p0[1], o0[4 + i]); o1[4 + i] = mfma16(v3[i], p1[1], o1[4 + i]); }
;   __builtin_amdgcn_s_setprio(0);
; }
; DI void pack_p(const f32x4 (&s)[4], bf16x8 (&pf)[2]) {
; #pragma unroll
;   for (int s2 = 0; s2 < 2; ++s2)
;     pf[s2] = mk8(pk2(s[2 * s2][0], s[2 * s2][1]), pk2(s[2 * s2][2], s[2 * s2][3]),
;                  pk2(s[2 * s2 + 1][0], s[2 * s2 + 1][1]), pk2(s[2 * s2 + 1][2], s[2 * s2 + 1][3]));
; }
.LBB0_569:
	s_or_b64 exec, exec, s[50:51]
	v_add_f32_e32 v219, v219, v231
	v_cvt_pk_bf16_f32 v0, v0, v1
	v_cvt_pk_bf16_f32 v1, v2, v3
	v_cvt_pk_bf16_f32 v2, v4, v5
	v_cvt_pk_bf16_f32 v3, v6, v7
	v_cvt_pk_bf16_f32 v4, v8, v9
	v_cvt_pk_bf16_f32 v5, v10, v11
	v_cvt_pk_bf16_f32 v6, v12, v13
	v_cvt_pk_bf16_f32 v7, v14, v15
	v_cvt_pk_bf16_f32 v8, v16, v17
	v_cvt_pk_bf16_f32 v9, v18, v19
	v_cvt_pk_bf16_f32 v10, v20, v21
	v_cvt_pk_bf16_f32 v11, v22, v23
	v_cvt_pk_bf16_f32 v12, v24, v25
	v_cvt_pk_bf16_f32 v13, v26, v27
	v_cvt_pk_bf16_f32 v14, v28, v29
	v_cvt_pk_bf16_f32 v15, v30, v31
	v_add3_u32 v144, s67, v218, v216
	ds_read_b128 v[16:19], v144 offset:16384
	ds_read_b128 v[20:23], v144 offset:18432
	ds_read_b128 v[24:27], v144 offset:20480
	ds_read_b128 v[28:31], v144 offset:22528
	s_waitcnt lgkmcnt(4)
	v_mfma_f32_16x16x32_bf16 v[92:95], v[140:143], v[0:3], v[92:95]
	v_mfma_f32_16x16x32_bf16 v[60:63], v[140:143], v[8:11], v[60:63]
	v_mfma_f32_16x16x32_bf16 v[88:91], v[136:139], v[0:3], v[88:91]
	v_mfma_f32_16x16x32_bf16 v[56:59], v[136:139], v[8:11], v[56:59]
	v_mfma_f32_16x16x32_bf16 v[84:87], v[128:131], v[0:3], v[84:87]
	v_mfma_f32_16x16x32_bf16 v[52:55], v[128:131], v[8:11], v[52:55]
	v_mfma_f32_16x16x32_bf16 v[80:83], v[120:123], v[0:3], v[80:83]
	v_mfma_f32_16x16x32_bf16 v[48:51], v[120:123], v[8:11], v[48:51]
	s_nop 0
	ds_read_b128 v[120:123], v144 offset:24576
	ds_read_b128 v[128:131], v144 offset:26624
	ds_read_b128 v[136:139], v144 offset:28672
	ds_read_b128 v[140:143], v144 offset:30720
	v_mfma_f32_16x16x32_bf16 v[76:79], v[132:135], v[0:3], v[76:79]
	v_mfma_f32_16x16x32_bf16 v[44:47], v[132:135], v[8:11], v[44:47]
	v_mfma_f32_16x16x32_bf16 v[72:75], v[124:127], v[0:3], v[72:75]
	v_mfma_f32_16x16x32_bf16 v[40:43], v[124:127], v[8:11], v[40:43]
	v_mfma_f32_16x16x32_bf16 v[68:71], v[116:119], v[0:3], v[68:71]
	v_mfma_f32_16x16x32_bf16 v[36:39], v[116:119], v[8:11], v[36:39]
	v_mfma_f32_16x16x32_bf16 v[0:3], v[112:115], v[0:3], v[64:67]
	v_mfma_f32_16x16x32_bf16 v[8:11], v[112:115], v[8:11], v[32:35]
	s_nop 0
	s_waitcnt lgkmcnt(7)
	v_mfma_f32_16x16x32_bf16 v[92:95], v[16:19], v[4:7], v[92:95]
	v_mfma_f32_16x16x32_bf16 v[60:63], v[16:19], v[12:15], v[60:63]
	s_waitcnt lgkmcnt(6)
	v_mfma_f32_16x16x32_bf16 v[88:91], v[20:23], v[4:7], v[88:91]
	v_mfma_f32_16x16x32_bf16 v[56:59], v[20:23], v[12:15], v[56:59]
	s_waitcnt lgkmcnt(5)
	v_mfma_f32_16x16x32_bf16 v[84:87], v[24:27], v[4:7], v[84:87]
	v_mfma_f32_16x16x32_bf16 v[52:55], v[24:27], v[12:15], v[52:55]
	s_waitcnt lgkmcnt(4)
	v_mfma_f32_16x16x32_bf16 v[80:83], v[28:31], v[4:7], v[80:83]
	v_mfma_f32_16x16x32_bf16 v[48:51], v[28:31], v[12:15], v[48:51]
	s_nop 0
	s_waitcnt lgkmcnt(3)
	v_mfma_f32_16x16x32_bf16 v[76:79], v[120:123], v[4:7], v[76:79]
	v_mfma_f32_16x16x32_bf16 v[44:47], v[120:123], v[12:15], v[44:47]
	s_waitcnt lgkmcnt(2)
	v_mfma_f32_16x16x32_bf16 v[72:75], v[128:131], v[4:7], v[72:75]
	v_mfma_f32_16x16x32_bf16 v[40:43], v[128:131], v[12:15], v[40:43]
	s_waitcnt lgkmcnt(1)
	v_mfma_f32_16x16x32_bf16 v[68:71], v[136:139], v[4:7], v[68:71]
	v_mfma_f32_16x16x32_bf16 v[36:39], v[136:139], v[12:15], v[36:39]
	s_waitcnt lgkmcnt(0)
	v_mfma_f32_16x16x32_bf16 v[64:67], v[140:143], v[4:7], v[0:3]
	v_mfma_f32_16x16x32_bf16 v[32:35], v[140:143], v[12:15], v[8:11]
	s_nop 0

; DI float ex2(float x) { return __builtin_amdgcn_exp2f(x); }
; #define SB0 __builtin_amdgcn_sched_barrier(0)
; template <bool MASKED, class MF>
; DI void flash_update(f32x4 (&s)[4], float scl, float& mx, float& ls, f32x4 (&o)[8], MF maskfn, bool lane_on) {
;   float tmax = -1e30f;
; #pragma unroll
;   for (int kt = 0; kt < 4; ++kt)
; #pragma unroll
;     for (int i = 0; i < 4; ++i) {
;       if (MASKED) { if (maskfn(kt, i)) s[kt][i] = -1e30f; }
;       tmax = fmaxf(tmax, s[kt][i]);
;     }
;   tmax = rowmax4(tmax);
;   if (!lane_on) tmax = -1e30f;
;   const float th = 8.f / scl;
;   if (__any(tmax > mx + th)) {
;     const float mnew = fmaxf(mx, tmax);
;     const float alpha = ex2((mx - mnew) * scl);
;     ls *= alpha;
; #pragma unroll
;     for (int dt = 0; dt < 8; ++dt) o[dt] *= alpha;
;     mx = mnew;
;   }
; DI void ldk2m(bf16x8 (&k)[2], const char* Kb, int m, int kt, int lr, int quad) {
; #pragma unroll
;   for (int kk = 0; kk < 2; ++kk) k[kk] = *(const bf16x8*)(Kb + (kt * 16 + lr) * 256 + (((m * 8 + kk * 4 + quad) ^ lr) << 4));
; }
; DI void diff_S2(f32x4 (&s0)[4], f32x4 (&s1)[4], const char* Kb, const char* Vb, int m, const bf16x8 (&q0)[2], const bf16x8 (&q1)[2],
;                 bf16x8 (&v0)[4], bf16x8 (&v1)[4], int lr, int quad) {
;   bf16x8 f0[2], f1[2], f2[2], f3[2];
;   ldk2m(f0, Kb, m, 0, lr, quad); ldk2m(f1, Kb, m, 1, lr, quad); SB0;
;   ldk2m(f2, Kb, m, 2, lr, quad); s0[0] = mma2(f0, q0); s1[0] = mma2(f0, q1); SB0;
;   ldk2m(f3, Kb, m, 3, lr, quad); s0[1] = mma2(f1, q0); s1[1] = mma2(f1, q1); SB0;
;   ldv4(v0, Vb, 0, lr, quad); s0[2] = mma2(f2, q0); s1[2] = mma2(f2, q1); SB0;
;   ldv4(v1, Vb, 1, lr, quad); s0[3] = mma2(f3, q0); s1[3] = mma2(f3, q1); SB0;
; }
.LBB0_571:
	s_cmp_eq_u32 s7, s63
	s_cbranch_scc1 .LBB0_582
	s_or_b32 s4, s7, s65
	s_lshl_b32 s6, s4, 6
	v_cmp_le_u32_e32 vcc, s6, v211
	s_and_saveexec_b64 s[48:49], vcc
	s_cbranch_execz .LBB0_570
	s_lshl_b32 s4, s7, 15
	s_add_i32 s67, s66, s4
	v_add_u32_e32 v0, s67, v212
	v_add_u32_e32 v28, v0, v214
	v_add_u32_e32 v29, v0, v215
	ds_read_b128 v[0:3], v28
	ds_read_b128 v[4:7], v28 offset:4096
	ds_read_b128 v[8:11], v29
	ds_read_b128 v[12:15], v29 offset:4096
	s_or_b32 s4, s6, 63
	v_cmp_le_u32_e32 vcc, s4, v207
	ds_read_b128 v[16:19], v28 offset:8192
	ds_read_b128 v[20:23], v29 offset:8192
	s_waitcnt lgkmcnt(5)
	v_mfma_f32_16x16x32_bf16 v[24:27], v[0:3], v[96:99], 0
	s_waitcnt lgkmcnt(3)
	v_mfma_f32_16x16x32_bf16 v[172:175], v[8:11], v[100:103], v[24:27]
	s_nop 0
	v_mfma_f32_16x16x32_bf16 v[0:3], v[0:3], v[104:107], 0
	v_mfma_f32_16x16x32_bf16 v[156:159], v[8:11], v[108:111], v[0:3]
	s_nop 0
	s_nop 5
	ds_read_b128 v[0:3], v28 offset:12288
	ds_read_b128 v[8:11], v29 offset:12288
	v_mfma_f32_16x16x32_bf16 v[24:27], v[4:7], v[96:99], 0
	s_waitcnt lgkmcnt(4)
	v_mfma_f32_16x16x32_bf16 v[164:167], v[12:15], v[100:103], v[24:27]
	s_nop 0
	v_mfma_f32_16x16x32_bf16 v[4:7], v[4:7], v[104:107], 0
	v_mfma_f32_16x16x32_bf16 v[148:151], v[12:15], v[108:111], v[4:7]
	s_nop 0
	v_add3_u32 v12, s67, v217, v216
	ds_read_b128 v[140:143], v12 offset:16384
	ds_read_b128 v[136:139], v12 offset:18432
	ds_read_b128 v[128:131], v12 offset:20480
	ds_read_b128 v[120:123], v12 offset:22528
	s_waitcnt lgkmcnt(7)
	v_mfma_f32_16x16x32_bf16 v[4:7], v[16:19], v[96:99], 0
	s_waitcnt lgkmcnt(6)
	v_mfma_f32_16x16x32_bf16 v[168:171], v[20:23], v[100:103], v[4:7]
	s_nop 0
	v_mfma_f32_16x16x32_bf16 v[4:7], v[16:19], v[104:107], 0
	v_mfma_f32_16x16x32_bf16 v[152:155], v[20:23], v[108:111], v[4:7]
	s_nop 0
	ds_read_b128 v[132:135], v12 offset:24576
	ds_read_b128 v[124:127], v12 offset:26624
	ds_read_b128 v[116:119], v12 offset:28672
	ds_read_b128 v[112:115], v12 offset:30720
	s_waitcnt lgkmcnt(9)
	v_mfma_f32_16x16x32_bf16 v[4:7], v[0:3], v[96:99], 0
	s_waitcnt lgkmcnt(8)
	v_mfma_f32_16x16x32_bf16 v[160:163], v[8:11], v[100:103], v[4:7]
	s_nop 0
	v_mfma_f32_16x16x32_bf16 v[0:3], v[0:3], v[104:107], 0
	v_mfma_f32_16x16x32_bf16 v[144:147], v[8:11], v[108:111], v[0:3]
	s_nop 0
	v_add_f32_e32 v232, 0x40b17218, v220
	s_and_saveexec_b64 s[4:5], vcc
	s_xor_b64 s[4:5], exec, s[4:5]
	s_cbranch_execz .LBB0_579
	s_nop 1
	v_max3_f32 v0, v172, s53, v173
	v_max3_f32 v0, v0, v174, v175
	v_max3_f32 v0, v0, v164, v165
	v_max3_f32 v0, v0, v166, v167
	v_max3_f32 v0, v0, v168, v169
	v_max3_f32 v0, v0, v170, v171
	v_max3_f32 v0, v0, v160, v161
	v_max3_f32 v0, v0, v162, v163
	v_mov_b32_e32 v1, v0
	s_nop 1
	v_permlane16_swap_b32_e32 v0, v1
	v_max_f32_e32 v1, v1, v1
	v_max_f32_e32 v0, v0, v0
	v_max_f32_e32 v0, v0, v1
	v_mov_b32_e32 v1, v0
	s_nop 1
	v_permlane32_swap_b32_e32 v0, v1
	v_max_f32_e32 v1, v1, v1
	v_max_f32_e32 v0, v0, v0
	v_max_f32_e32 v0, v0, v1
	v_cmp_gt_f32_e32 vcc, v0, v232
	s_cbranch_vccz .LBB0_576
	v_max_f32_e32 v0, v0, v0
	v_max_f32_e32 v1, v220, v220
	v_max_f32_e32 v1, v1, v0
	v_sub_f32_e32 v0, v220, v1
	v_mul_f32_e32 v0, 0x3fb8aa3b, v0
	v_exp_f32_e32 v0, v0
	v_mov_b32_e32 v220, v1
	v_mul_f32_e32 v213, v213, v0
	v_pk_mul_f32 v[94:95], v[94:95], v[0:1] op_sel_hi:[1,0]
	v_pk_mul_f32 v[92:93], v[92:93], v[0:1] op_sel_hi:[1,0]
	v_pk_mul_f32 v[90:91], v[90:91], v[0:1] op_sel_hi:[1,0]
	v_pk_mul_f32 v[88:89], v[88:89], v[0:1] op_sel_hi:[1,0]
	v_pk_mul_f32 v[86:87], v[86:87], v[0:1] op_sel_hi:[1,0]
	v_pk_mul_f32 v[84:85], v[84:85], v[0:1] op_sel_hi:[1,0]
	v_pk_mul_f32 v[82:83], v[82:83], v[0:1] op_sel_hi:[1,0]
	v_pk_mul_f32 v[80:81], v[80:81], v[0:1] op_sel_hi:[1,0]
	v_pk_mul_f32 v[78:79], v[78:79], v[0:1] op_sel_hi:[1,0]
	v_pk_mul_f32 v[76:77], v[76:77], v[0:1] op_sel_hi:[1,0]
	v_pk_mul_f32 v[74:75], v[74:75], v[0:1] op_sel_hi:[1,0]
	v_pk_mul_f32 v[72:73], v[72:73], v[0:1] op_sel_hi:[1,0]
	v_pk_mul_f32 v[70:71], v[70:71], v[0:1] op_sel_hi:[1,0]
	v_pk_mul_f32 v[68:69], v[68:69], v[0:1] op_sel_hi:[1,0]
	v_pk_mul_f32 v[66:67], v[66:67], v[0:1] op_sel_hi:[1,0]
	v_pk_mul_f32 v[64:65], v[64:65], v[0:1] op_sel_hi:[1,0]

; DI f32x4 mfma16(bf16x8 a, bf16x8 b, f32x4 c) { return __builtin_amdgcn_mfma_f32_16x16x32_bf16(a, b, c, 0, 0, 0); }
; #define SB0 __builtin_amdgcn_sched_barrier(0)
; DI void ldk4(bf16x8 (&k)[4], const char* Kb, int kt, int lr, int quad) {
; #pragma unroll
;   for (int kk = 0; kk < 4; ++kk) k[kk] = *(const bf16x8*)(Kb + (kt * 16 + lr) * 256 + (((kk * 4 + quad) ^ lr) << 4));
; }
; DI f32x4 mma4(const bf16x8 (&k)[4], const bf16x8 (&qf)[4]) {
;   f32x4 a = zero4();
;   __builtin_amdgcn_s_setprio(1);
; #pragma unroll
;   for (int kk = 0; kk < 4; ++kk) a = mfma16(k[kk], qf[kk], a);
;   __builtin_amdgcn_s_setprio(0);
;   return a;
; }
; DI void ldv4(bf16x8 (&v)[4], const char* Vb, int qtr, int lr, int quad) {
; #pragma unroll
;   for (int i = 0; i < 4; ++i) v[i] = load_vfrag(Vb, qtr >> 1, 4 * (qtr & 1) + i, lr, quad);
; }
; DI void nsa_S(f32x4 (&s)[4], const char* Kb, const char* Vb, const bf16x8 (&qf)[4], bf16x8 (&v0)[4], int lr, int quad) {
;   bf16x8 k0[4], k1[4], k2[4], k3[4];
;   ldk4(k0, Kb, 0, lr, quad); SB0;
;   ldk4(k1, Kb, 1, lr, quad); s[0] = mma4(k0, qf); SB0;
;   ldk4(k2, Kb, 2, lr, quad); s[1] = mma4(k1, qf); SB0;
;   ldk4(k3, Kb, 3, lr, quad); s[2] = mma4(k2, qf); SB0;
;   ldv4(v0, Vb, 0, lr, quad); s[3] = mma4(k3, qf); SB0;
; }
.LBB0_752:
	v_lshl_add_u32 v14, s13, 15, v9
	v_add_u32_e32 v15, v14, v235
	v_add_u32_e32 v67, v14, v237
	v_add_u32_e32 v66, v14, v236
	ds_read_b128 v[10:13], v15
	ds_read_b128 v[34:37], v66
	v_add_u32_e32 v14, v14, v238
	ds_read_b128 v[38:41], v67
	ds_read_b128 v[42:45], v14
	s_xor_b64 s[10:11], s[10:11], -1
	ds_read_b128 v[46:49], v15 offset:4096
	ds_read_b128 v[50:53], v66 offset:4096
	ds_read_b128 v[54:57], v67 offset:4096
	ds_read_b128 v[58:61], v14 offset:4096
	s_waitcnt lgkmcnt(7)
	v_mfma_f32_16x16x32_bf16 v[10:13], v[10:13], v[18:21], 0
	s_waitcnt lgkmcnt(6)
	v_mfma_f32_16x16x32_bf16 v[10:13], v[34:37], v[22:25], v[10:13]
	s_waitcnt lgkmcnt(5)
	v_mfma_f32_16x16x32_bf16 v[10:13], v[38:41], v[26:29], v[10:13]
	s_waitcnt lgkmcnt(4)
	v_mfma_f32_16x16x32_bf16 v[10:13], v[42:45], v[30:33], v[10:13]
	s_nop 0
	ds_read_b128 v[34:37], v15 offset:8192
	ds_read_b128 v[38:41], v66 offset:8192
	ds_read_b128 v[42:45], v67 offset:8192
	ds_read_b128 v[62:65], v14 offset:8192
	s_waitcnt lgkmcnt(7)
	v_mfma_f32_16x16x32_bf16 v[46:49], v[46:49], v[18:21], 0
	s_waitcnt lgkmcnt(6)
	v_mfma_f32_16x16x32_bf16 v[46:49], v[50:53], v[22:25], v[46:49]
	s_waitcnt lgkmcnt(5)
	v_mfma_f32_16x16x32_bf16 v[46:49], v[54:57], v[26:29], v[46:49]
	s_waitcnt lgkmcnt(4)
	v_mfma_f32_16x16x32_bf16 v[46:49], v[58:61], v[30:33], v[46:49]
	s_nop 0
	ds_read_b128 v[50:53], v15 offset:12288
	ds_read_b128 v[54:57], v66 offset:12288
	ds_read_b128 v[58:61], v67 offset:12288
	ds_read_b128 v[66:69], v14 offset:12288
	s_waitcnt lgkmcnt(7)
	v_mfma_f32_16x16x32_bf16 v[34:37], v[34:37], v[18:21], 0
	s_waitcnt lgkmcnt(6)
	v_mfma_f32_16x16x32_bf16 v[34:37], v[38:41], v[22:25], v[34:37]
	s_waitcnt lgkmcnt(5)
	v_mfma_f32_16x16x32_bf16 v[34:37], v[42:45], v[26:29], v[34:37]
	s_waitcnt lgkmcnt(4)
	v_mfma_f32_16x16x32_bf16 v[34:37], v[62:65], v[30:33], v[34:37]
	s_nop 0
	s_waitcnt lgkmcnt(3)
	v_mfma_f32_16x16x32_bf16 v[38:41], v[50:53], v[18:21], 0
	s_waitcnt lgkmcnt(2)
	v_mfma_f32_16x16x32_bf16 v[38:41], v[54:57], v[22:25], v[38:41]
	s_waitcnt lgkmcnt(1)
	v_mfma_f32_16x16x32_bf16 v[38:41], v[58:61], v[26:29], v[38:41]
	s_waitcnt lgkmcnt(0)
; DI float ex2(float x) { return __builtin_amdgcn_exp2f(x); }
; DI void nsa_item(const Params& p, int b, int g, int qb, char* smem, int tid) {
;     ...
;     float tmax = -1e30f;
; #pragma unroll
;     for (int kt = 0; kt < 4; ++kt)
; #pragma unroll
;       for (int i = 0; i < 4; ++i) {
;         int cc = j * 64 + kt * 16 + quad * 4 + i;
;         float v = (cc <= cmax) ? s[kt][i] * SCL : -1e30f;
;         s[kt][i] = v; tmax = fmaxf(tmax, v);
;       }
;     tmax = rowmax4(tmax);
;     float mnew = fmaxf(mx, tmax), rs = 0.f;
; #pragma unroll
;     for (int kt = 0; kt < 4; ++kt)
; #pragma unroll
;       for (int i = 0; i < 4; ++i) { float v = s[kt][i]; rs += (v > -1e29f) ? ex2(v - mnew) : 0.f; }
;     ls = ls * ex2(mx - mnew) + rs; mx = mnew;
	v_mfma_f32_16x16x32_bf16 v[38:41], v[66:69], v[30:33], v[38:41]
	s_nop 0
	v_lshl_or_b32 v14, s12, 6, v214
	v_mul_f32_e32 v10, 0x3e0293ee, v10
	v_cmp_le_i32_e32 vcc, v14, v78
	v_mul_f32_e32 v11, 0x3e0293ee, v11
	v_or_b32_e32 v15, 2, v14
	v_cndmask_b32_e32 v10, v231, v10, vcc
	v_cmp_lt_i32_e32 vcc, v14, v78
	v_mul_f32_e32 v12, 0x3e0293ee, v12
	v_mul_f32_e32 v13, 0x3e0293ee, v13
	v_cndmask_b32_e32 v11, v231, v11, vcc
	v_cmp_le_i32_e32 vcc, v15, v78
	v_or_b32_e32 v15, 3, v14
	v_mul_f32_e32 v42, 0x3e0293ee, v46
	v_cndmask_b32_e32 v12, v231, v12, vcc
	v_cmp_le_i32_e32 vcc, v15, v78
	v_or_b32_e32 v15, 16, v14
	v_mul_f32_e32 v43, 0x3e0293ee, v47
	v_cndmask_b32_e32 v13, v231, v13, vcc
	v_cmp_le_i32_e32 vcc, v15, v78
	v_mul_f32_e32 v44, 0x3e0293ee, v48
	v_mul_f32_e32 v45, 0x3e0293ee, v49
	v_cndmask_b32_e32 v15, v231, v42, vcc
	v_or_b32_e32 v42, 17, v14
	v_cmp_le_i32_e32 vcc, v42, v78
	v_mul_f32_e32 v34, 0x3e0293ee, v34
	v_mul_f32_e32 v35, 0x3e0293ee, v35
	v_cndmask_b32_e32 v42, v231, v43, vcc
	v_or_b32_e32 v43, 18, v14
	v_cmp_le_i32_e32 vcc, v43, v78
	v_mul_f32_e32 v36, 0x3e0293ee, v36
	v_mul_f32_e32 v37, 0x3e0293ee, v37
	v_cndmask_b32_e32 v43, v231, v44, vcc
	v_or_b32_e32 v44, 19, v14
	v_cmp_le_i32_e32 vcc, v44, v78
	v_mul_f32_e32 v38, 0x3e0293ee, v38
	v_mul_f32_e32 v39, 0x3e0293ee, v39
	v_cndmask_b32_e32 v44, v231, v45, vcc
	v_or_b32_e32 v45, 32, v14
	v_cmp_le_i32_e32 vcc, v45, v78
	v_or_b32_e32 v45, 33, v14
	v_mul_f32_e32 v40, 0x3e0293ee, v40
	v_cndmask_b32_e32 v34, v231, v34, vcc
	v_cmp_le_i32_e32 vcc, v45, v78
	v_or_b32_e32 v45, 34, v14
	v_mul_f32_e32 v41, 0x3e0293ee, v41
	v_cndmask_b32_e32 v35, v231, v35, vcc
	v_cmp_le_i32_e32 vcc, v45, v78
	v_or_b32_e32 v45, 35, v14
	s_nop 0
	v_cndmask_b32_e32 v36, v231, v36, vcc
	v_cmp_le_i32_e32 vcc, v45, v78
	v_or_b32_e32 v45, 48, v14
	s_nop 0
	v_cndmask_b32_e32 v37, v231, v37, vcc
	v_cmp_le_i32_e32 vcc, v45, v78
	v_or_b32_e32 v45, 49, v14
	s_nop 0
	v_cndmask_b32_e32 v38, v231, v38, vcc
	v_cmp_le_i32_e32 vcc, v45, v78
	v_or_b32_e32 v45, 50, v14
	v_or_b32_e32 v14, 51, v14
	v_cndmask_b32_e32 v39, v231, v39, vcc
	v_cmp_le_i32_e32 vcc, v45, v78
	s_nop 1
	v_cndmask_b32_e32 v40, v231, v40, vcc
	v_cmp_le_i32_e32 vcc, v14, v78
	s_nop 1
	v_cndmask_b32_e32 v14, v231, v41, vcc
	v_max3_f32 v41, v10, s41, v11
	v_max3_f32 v41, v41, v12, v13
	v_max3_f32 v41, v41, v15, v42
	v_max3_f32 v41, v41, v43, v44
	v_max3_f32 v41, v41, v34, v35
	v_max3_f32 v41, v41, v36, v37
	v_max3_f32 v41, v41, v38, v39
	v_max3_f32 v41, v41, v40, v14
	v_mov_b32_e32 v45, v41
	s_nop 1
	v_permlane16_swap_b32_e32 v41, v45
	v_max_f32_e32 v45, v45, v45
	v_max_f32_e32 v41, v41, v41
	v_max_f32_e32 v41, v41, v45
	v_mov_b32_e32 v45, v41
	s_nop 1
	v_permlane32_swap_b32_e32 v41, v45
	v_max3_f32 v41, v94, v41, v45
	v_sub_f32_e32 v45, v10, v41
	v_exp_f32_e32 v45, v45
	v_cmp_lt_f32_e32 vcc, s33, v10
	v_sub_f32_e32 v46, v12, v41
	v_exp_f32_e32 v46, v46
	v_add_f32_e32 v45, 0, v45
	v_cndmask_b32_e32 v10, 0, v45, vcc
	v_sub_f32_e32 v45, v11, v41
	v_exp_f32_e32 v45, v45
	v_cmp_lt_f32_e32 vcc, s33, v11
	s_nop 1
	v_cndmask_b32_e32 v11, 0, v45, vcc
	v_cmp_lt_f32_e32 vcc, s33, v12
	v_add_f32_e32 v10, v11, v10
	v_sub_f32_e32 v12, v15, v41
	v_cndmask_b32_e32 v11, 0, v46, vcc
	v_add_f32_e32 v10, v11, v10
	v_sub_f32_e32 v11, v13, v41
	v_exp_f32_e32 v11, v11
	v_exp_f32_e32 v12, v12
	v_cmp_lt_f32_e32 vcc, s33, v13
	s_nop 1
	v_cndmask_b32_e32 v11, 0, v11, vcc
	v_cmp_lt_f32_e32 vcc, s33, v15
	v_add_f32_e32 v10, v11, v10
	s_nop 0
	v_cndmask_b32_e32 v11, 0, v12, vcc
	v_add_f32_e32 v10, v11, v10
	v_sub_f32_e32 v11, v42, v41
	v_exp_f32_e32 v11, v11
	v_sub_f32_e32 v12, v43, v41
	v_exp_f32_e32 v12, v12
	v_cmp_lt_f32_e32 vcc, s33, v42
	s_nop 1
	v_cndmask_b32_e32 v11, 0, v11, vcc
	v_cmp_lt_f32_e32 vcc, s33, v43
	v_add_f32_e32 v10, v11, v10
	s_nop 0
	v_cndmask_b32_e32 v11, 0, v12, vcc
	v_add_f32_e32 v10, v11, v10
	v_sub_f32_e32 v11, v44, v41
	v_exp_f32_e32 v11, v11
	v_sub_f32_e32 v12, v34, v41
	v_exp_f32_e32 v12, v12
	v_cmp_lt_f32_e32 vcc, s33, v44
	s_nop 1
	v_cndmask_b32_e32 v11, 0, v11, vcc
	v_cmp_lt_f32_e32 vcc, s33, v34
	v_add_f32_e32 v10, v11, v10
	s_nop 0
	v_cndmask_b32_e32 v11, 0, v12, vcc
	v_add_f32_e32 v10, v11, v10
	v_sub_f32_e32 v11, v35, v41
	v_exp_f32_e32 v11, v11
	v_sub_f32_e32 v12, v36, v41
	v_exp_f32_e32 v12, v12
	v_cmp_lt_f32_e32 vcc, s33, v35
	s_nop 1
	v_cndmask_b32_e32 v11, 0, v11, vcc
	v_cmp_lt_f32_e32 vcc, s33, v36
	v_add_f32_e32 v10, v11, v10
	s_nop 0
	v_cndmask_b32_e32 v11, 0, v12, vcc
	v_add_f32_e32 v10, v11, v10
	v_sub_f32_e32 v11, v37, v41
	v_exp_f32_e32 v11, v11
	v_sub_f32_e32 v12, v38, v41
	v_exp_f32_e32 v12, v12
	v_cmp_lt_f32_e32 vcc, s33, v37
	s_nop 1
	v_cndmask_b32_e32 v11, 0, v11, vcc
	v_cmp_lt_f32_e32 vcc, s33, v38
	v_add_f32_e32 v10, v11, v10
	s_nop 0
	v_cndmask_b32_e32 v11, 0, v12, vcc
	v_add_f32_e32 v10, v11, v10
	v_sub_f32_e32 v11, v39, v41
	v_exp_f32_e32 v11, v11
	v_sub_f32_e32 v12, v40, v41
	v_exp_f32_e32 v12, v12
	v_cmp_lt_f32_e32 vcc, s33, v39
	s_nop 1
	v_cndmask_b32_e32 v11, 0, v11, vcc
	v_cmp_lt_f32_e32 vcc, s33, v40
	v_add_f32_e32 v10, v11, v10
	s_nop 0
	v_cndmask_b32_e32 v11, 0, v12, vcc
	v_add_f32_e32 v10, v11, v10
	v_sub_f32_e32 v11, v14, v41
	v_exp_f32_e32 v11, v11
	v_sub_f32_e32 v12, v94, v41
	v_exp_f32_e32 v12, v12
	v_cmp_lt_f32_e32 vcc, s33, v14
	v_mov_b32_e32 v94, v41
	s_nop 0
	v_cndmask_b32_e32 v11, 0, v11, vcc
	v_add_f32_e32 v10, v11, v10
	v_fmac_f32_e32 v10, v7, v12
	v_mov_b32_e32 v7, v10
	s_mov_b32 s13, 1
	s_andn2_b64 vcc, exec, s[10:11]
	s_mov_b64 s[10:11], 0
	s_cbranch_vccz .LBB0_755

; DI float ex2(float x) { return __builtin_amdgcn_exp2f(x); }
; #define SB0 __builtin_amdgcn_sched_barrier(0)
; DI void nsa_S(f32x4 (&s)[4], const char* Kb, const char* Vb, const bf16x8 (&qf)[4], bf16x8 (&v0)[4], int lr, int quad) {
;   bf16x8 k0[4], k1[4], k2[4], k3[4];
;   ldk4(k0, Kb, 0, lr, quad); SB0;
;   ldk4(k1, Kb, 1, lr, quad); s[0] = mma4(k0, qf); SB0;
;   ldk4(k2, Kb, 2, lr, quad); s[1] = mma4(k1, qf); SB0;
;   ldk4(k3, Kb, 3, lr, quad); s[2] = mma4(k2, qf); SB0;
;   ldv4(v0, Vb, 0, lr, quad); s[3] = mma4(k3, qf); SB0;
; }
; DI void nsa_item(const Params& p, int b, int g, int qb, char* smem, int tid) {
;     ...
;     float* irow = imp + qi * 132;
; #pragma unroll
;     for (int kt = 0; kt < 4; ++kt) {
;       float a = 0.f;
; #pragma unroll
;       for (int i = 0; i < 4; ++i) {
;         int cc = j * 64 + kt * 16 + quad * 4 + i;
;         float pv = (cc <= cmax) ? ex2(s[kt][i] * SCL - mx) * inv : 0.f;
;         s[kt][i] = pv; a += pv;
;       }
;       if (a != 0.f) {
;         int n1 = j * 16 + kt * 4 + quad;
;         atomicAdd(irow + n1, a);
;         if (s[kt][3] != 0.f) atomicAdd(irow + n1 + 1, s[kt][3]);
;       }
;     }
.LBB0_768:
	s_or_b32 s10, s17, s15
	s_cmp_ge_u32 s10, s14
	s_cbranch_scc1 .LBB0_767
	s_lshl_b32 s11, s17, 15
	s_add_i32 s17, s16, s11
	v_add_u32_e32 v8, s17, v234
	v_add_u32_e32 v104, v8, v235
	v_add_u32_e32 v108, v8, v237
	v_add_u32_e32 v105, v8, v236
	ds_read_b128 v[0:3], v104
	ds_read_b128 v[4:7], v105
	v_add_u32_e32 v112, v8, v238
	ds_read_b128 v[8:11], v108
	ds_read_b128 v[12:15], v112
	ds_read_b128 v[66:69], v104 offset:4096
	ds_read_b128 v[70:73], v105 offset:4096
	ds_read_b128 v[74:77], v108 offset:4096
	ds_read_b128 v[96:99], v112 offset:4096
	s_waitcnt lgkmcnt(7)
	v_mfma_f32_16x16x32_bf16 v[0:3], v[0:3], v[18:21], 0
	s_waitcnt lgkmcnt(6)
	v_mfma_f32_16x16x32_bf16 v[0:3], v[4:7], v[22:25], v[0:3]
	s_waitcnt lgkmcnt(5)
	v_mfma_f32_16x16x32_bf16 v[0:3], v[8:11], v[26:29], v[0:3]
	s_waitcnt lgkmcnt(4)
	v_mfma_f32_16x16x32_bf16 v[100:103], v[12:15], v[30:33], v[0:3]
	s_nop 0
	s_nop 5
	ds_read_b128 v[0:3], v104 offset:8192
	ds_read_b128 v[4:7], v105 offset:8192
	ds_read_b128 v[8:11], v108 offset:8192
	ds_read_b128 v[12:15], v112 offset:8192
	s_waitcnt lgkmcnt(7)
	v_mfma_f32_16x16x32_bf16 v[66:69], v[66:69], v[18:21], 0
	s_waitcnt lgkmcnt(6)
	v_mfma_f32_16x16x32_bf16 v[66:69], v[70:73], v[22:25], v[66:69]
	s_waitcnt lgkmcnt(5)
	v_mfma_f32_16x16x32_bf16 v[66:69], v[74:77], v[26:29], v[66:69]
	s_waitcnt lgkmcnt(4)
	v_mfma_f32_16x16x32_bf16 v[74:77], v[96:99], v[30:33], v[66:69]
	s_nop 0
	s_nop 5
	ds_read_b128 v[66:69], v104 offset:12288
	ds_read_b128 v[104:107], v105 offset:12288
	ds_read_b128 v[108:111], v108 offset:12288
	ds_read_b128 v[112:115], v112 offset:12288
	s_waitcnt lgkmcnt(7)
	v_mfma_f32_16x16x32_bf16 v[0:3], v[0:3], v[18:21], 0
	s_waitcnt lgkmcnt(6)
	v_mfma_f32_16x16x32_bf16 v[0:3], v[4:7], v[22:25], v[0:3]
	s_waitcnt lgkmcnt(5)
	v_mfma_f32_16x16x32_bf16 v[0:3], v[8:11], v[26:29], v[0:3]
	s_waitcnt lgkmcnt(4)
	v_mfma_f32_16x16x32_bf16 v[70:73], v[12:15], v[30:33], v[0:3]
	s_nop 0
	s_nop 5
	v_add_u32_e32 v0, s17, v242
	v_add_u32_e32 v96, v0, v241
	ds_read_b128 v[0:3], v96 offset:16384
	ds_read_b128 v[4:7], v96 offset:18432
	ds_read_b128 v[8:11], v96 offset:20480
	ds_read_b128 v[12:15], v96 offset:22528
	s_waitcnt lgkmcnt(7)
	v_mfma_f32_16x16x32_bf16 v[66:69], v[66:69], v[18:21], 0
	s_waitcnt lgkmcnt(6)
	v_mfma_f32_16x16x32_bf16 v[66:69], v[104:107], v[22:25], v[66:69]
	s_waitcnt lgkmcnt(5)
	v_mfma_f32_16x16x32_bf16 v[66:69], v[108:111], v[26:29], v[66:69]
	s_waitcnt lgkmcnt(4)
	v_mfma_f32_16x16x32_bf16 v[66:69], v[112:115], v[30:33], v[66:69]
	s_nop 0
	v_fma_f32 v97, v100, s40, -v94
	v_exp_f32_e32 v97, v97
	v_fma_f32 v98, v101, s40, -v94
	v_exp_f32_e32 v98, v98
	s_lshl_b32 s18, s10, 6
	v_fma_f32 v100, v102, s40, -v94
	v_fma_f32 v101, v103, s40, -v94
	v_or_b32_e32 v99, s18, v214
	v_exp_f32_e32 v100, v100
	v_exp_f32_e32 v101, v101
	v_mul_f32_e32 v97, v86, v97
	v_cmp_le_i32_e32 vcc, v99, v78
	v_mul_f32_e32 v98, v86, v98
	v_or_b32_e32 v103, 3, v99
	v_cndmask_b32_e32 v97, 0, v97, vcc
	v_cmp_lt_i32_e32 vcc, v99, v78
	v_add_f32_e32 v104, 0, v97
	v_pk_mul_f32 v[100:101], v[86:87], v[100:101]
	v_cndmask_b32_e32 v98, 0, v98, vcc
	v_add_f32_e32 v102, v98, v104
	v_or_b32_e32 v104, 2, v99
	v_cmp_le_i32_e32 vcc, v103, v79
	s_lshl_b32 s10, s10, 4
	s_nop 0
	v_cndmask_b32_e32 v99, 0, v101, vcc
	v_cmp_le_i32_e32 vcc, v104, v78
	s_nop 1
	v_cndmask_b32_e32 v100, 0, v100, vcc
	v_add_f32_e32 v101, v100, v102
	v_add_f32_e32 v102, v99, v101
	v_cmp_neq_f32_e32 vcc, 0, v102
	v_lshl_add_u32 v101, s10, 2, v95
	s_and_saveexec_b64 s[10:11], vcc
	s_cbranch_execz .LBB0_772
	s_waitcnt vmcnt(0)
	ds_add_f32 v101, v102
	v_cmp_neq_f32_e32 vcc, 0, v99
	s_and_b64 exec, exec, vcc
	ds_add_f32 v101, v99 offset:4

; DI f32x4 mfma16(bf16x8 a, bf16x8 b, f32x4 c) { return __builtin_amdgcn_mfma_f32_16x16x32_bf16(a, b, c, 0, 0, 0); }
; #define SB0 __builtin_amdgcn_sched_barrier(0)
; DI void nsa_PV(f32x4 (&o)[8], const char* Vb, const bf16x8 (&pf)[2], bf16x8 (&v0)[4], int lr, int quad) {
;   bf16x8 v1[4], v2[4], v3[4];
;   SB0;
;   ldv4(v1, Vb, 1, lr, quad);
;   __builtin_amdgcn_s_setprio(1);
; #pragma unroll
;   for (int i = 0; i < 4; ++i) o[i] = mfma16(v0[i], pf[0], o[i]);
;   __builtin_amdgcn_s_setprio(0);
;   SB0;
;   ldv4(v2, Vb, 2, lr, quad);
;   __builtin_amdgcn_s_setprio(1);
; #pragma unroll
;   for (int i = 0; i < 4; ++i) o[4 + i] = mfma16(v1[i], pf[0], o[4 + i]);
;   __builtin_amdgcn_s_setprio(0);
;   SB0;
;   ldv4(v3, Vb, 3, lr, quad);
;   __builtin_amdgcn_s_setprio(1);
; #pragma unroll
;   for (int i = 0; i < 4; ++i) o[i] = mfma16(v2[i], pf[1], o[i]);
;   __builtin_amdgcn_s_setprio(0);
;   SB0;
;   __builtin_amdgcn_s_setprio(1);
; #pragma unroll
;   for (int i = 0; i < 4; ++i) o[4 + i] = mfma16(v3[i], pf[1], o[4 + i]);
;   __builtin_amdgcn_s_setprio(0);
; }
.LBB0_781:
	s_or_b64 exec, exec, s[10:11]
	s_xor_b64 s[10:11], s[8:9], -1
	v_cvt_pk_bf16_f32 v98, v97, v98
	v_cvt_pk_bf16_f32 v99, v100, v99
	v_cvt_pk_bf16_f32 v100, v74, v75
	v_cvt_pk_bf16_f32 v101, v77, v76
	v_cvt_pk_bf16_f32 v70, v70, v71
	v_cvt_pk_bf16_f32 v71, v73, v72
	v_cvt_pk_bf16_f32 v72, v66, v67
	v_cvt_pk_bf16_f32 v73, v69, v68
	ds_read_b128 v[66:69], v96 offset:24576
	ds_read_b128 v[74:77], v96 offset:26624
	ds_read_b128 v[102:105], v96 offset:28672
	ds_read_b128 v[106:109], v96 offset:30720
	s_waitcnt lgkmcnt(4)
	v_mfma_f32_16x16x32_bf16 v[0:3], v[0:3], v[98:101], v[62:65]
	v_mfma_f32_16x16x32_bf16 v[4:7], v[4:7], v[98:101], v[58:61]
	v_mfma_f32_16x16x32_bf16 v[8:11], v[8:11], v[98:101], v[54:57]
	v_mfma_f32_16x16x32_bf16 v[12:15], v[12:15], v[98:101], v[50:53]
	s_nop 0
	v_add3_u32 v58, s17, v243, v241
	s_nop 0
	ds_read_b128 v[50:53], v58 offset:16384
	ds_read_b128 v[54:57], v58 offset:18432
	ds_read_b128 v[110:113], v58 offset:20480
	ds_read_b128 v[114:117], v58 offset:22528
	s_waitcnt lgkmcnt(7)
	v_mfma_f32_16x16x32_bf16 v[46:49], v[66:69], v[98:101], v[46:49]
	s_waitcnt lgkmcnt(6)
	v_mfma_f32_16x16x32_bf16 v[42:45], v[74:77], v[98:101], v[42:45]
	s_waitcnt lgkmcnt(5)
	v_mfma_f32_16x16x32_bf16 v[38:41], v[102:105], v[98:101], v[38:41]
	s_waitcnt lgkmcnt(4)
	v_mfma_f32_16x16x32_bf16 v[34:37], v[106:109], v[98:101], v[34:37]
	s_nop 0
	ds_read_b128 v[66:69], v58 offset:24576
	ds_read_b128 v[74:77], v58 offset:26624
	ds_read_b128 v[96:99], v58 offset:28672
	ds_read_b128 v[100:103], v58 offset:30720
	s_waitcnt lgkmcnt(7)
	v_mfma_f32_16x16x32_bf16 v[62:65], v[50:53], v[70:73], v[0:3]
	s_waitcnt lgkmcnt(6)
	v_mfma_f32_16x16x32_bf16 v[58:61], v[54:57], v[70:73], v[4:7]
	s_waitcnt lgkmcnt(5)
	v_mfma_f32_16x16x32_bf16 v[54:57], v[110:113], v[70:73], v[8:11]
	s_waitcnt lgkmcnt(4)
	v_mfma_f32_16x16x32_bf16 v[50:53], v[114:117], v[70:73], v[12:15]
	s_nop 0
	s_waitcnt lgkmcnt(3)
	v_mfma_f32_16x16x32_bf16 v[46:49], v[66:69], v[70:73], v[46:49]
	s_waitcnt lgkmcnt(2)
	v_mfma_f32_16x16x32_bf16 v[42:45], v[74:77], v[70:73], v[42:45]
	s_waitcnt lgkmcnt(1)
	v_mfma_f32_16x16x32_bf16 v[38:41], v[96:99], v[70:73], v[38:41]
	s_waitcnt lgkmcnt(0)
	v_mfma_f32_16x16x32_bf16 v[34:37], v[100:103], v[70:73], v[34:37]
	s_nop 0
	s_mov_b32 s17, 1
	s_mov_b64 s[8:9], 0
	s_and_b64 vcc, exec, s[10:11]
	s_cbranch_vccz .LBB0_768

; #define SB0 __builtin_amdgcn_sched_barrier(0)
; DI void nsa_S(f32x4 (&s)[4], const char* Kb, const char* Vb, const bf16x8 (&qf)[4], bf16x8 (&v0)[4], int lr, int quad) {
;   bf16x8 k0[4], k1[4], k2[4], k3[4];
;   ldk4(k0, Kb, 0, lr, quad); SB0;
;   ldk4(k1, Kb, 1, lr, quad); s[0] = mma4(k0, qf); SB0;
;   ldk4(k2, Kb, 2, lr, quad); s[1] = mma4(k1, qf); SB0;
;   ldk4(k3, Kb, 3, lr, quad); s[2] = mma4(k2, qf); SB0;
;   ldv4(v0, Vb, 0, lr, quad); s[3] = mma4(k3, qf); SB0;
; }
; DI void nsa_item(const Params& p, int b, int g, int qb, char* smem, int tid) {
;     ...
;       const bool sb = (sel[qi * 4 + (j >> 5)] >> (j & 31)) & 1u;
;       if (!__any(sb)) return;
;       f32x4 s[4];
;       bf16x8 va[4];
;       nsa_S(s, Kb, Vb, qf, va, lr, quad);
;       auto mf = [&](int kt, int i) __attribute__((always_inline)) { return j * 64 + kt * 16 + quad * 4 + i > qp; };
;       if (j == cur) flash_update<true>(s, SCL, mx2, l2, o, mf, sb);
;       else flash_update<false>(s, SCL, mx2, l2, o, mf, sb);
.LBB0_817:
	s_or_b32 s59, s48, s56
	s_cmp_gt_u32 s59, s2
	s_cbranch_scc1 .LBB0_816
	s_and_b32 s38, s59, 31
	s_waitcnt lgkmcnt(0)
	v_mov_b32_e32 v0, v172
	v_lshrrev_b32_e32 v1, s59, v0
	v_bfe_u32 v0, v0, s38, 1
	v_and_b32_e32 v1, 1, v1
	v_cmp_ne_u32_e32 vcc, 0, v0
	v_cmp_eq_u32_e64 s[38:39], 1, v1
	s_cbranch_vccz .LBB0_829
	s_lshl_b32 s48, s48, 15
	s_add_i32 s58, s57, s48
	v_add_u32_e32 v8, s58, v234
	v_add_u32_e32 v122, v8, v235
	v_add_u32_e32 v124, v8, v237
	v_add_u32_e32 v123, v8, v236
	ds_read_b128 v[0:3], v122
	ds_read_b128 v[4:7], v123
	v_add_u32_e32 v125, v8, v238
	ds_read_b128 v[8:11], v124
	ds_read_b128 v[12:15], v125
	ds_read_b128 v[98:101], v122 offset:4096
	ds_read_b128 v[102:105], v123 offset:4096
	ds_read_b128 v[106:109], v124 offset:4096
	ds_read_b128 v[110:113], v125 offset:4096
	s_waitcnt lgkmcnt(7)
	v_mfma_f32_16x16x32_bf16 v[0:3], v[0:3], v[18:21], 0
	s_waitcnt lgkmcnt(6)
	v_mfma_f32_16x16x32_bf16 v[0:3], v[4:7], v[22:25], v[0:3]
	s_waitcnt lgkmcnt(5)
	v_mfma_f32_16x16x32_bf16 v[0:3], v[8:11], v[26:29], v[0:3]
	s_waitcnt lgkmcnt(4)
	v_mfma_f32_16x16x32_bf16 v[114:117], v[12:15], v[30:33], v[0:3]
	s_nop 0
	s_nop 5
	ds_read_b128 v[0:3], v122 offset:8192
	ds_read_b128 v[4:7], v123 offset:8192
	ds_read_b128 v[8:11], v124 offset:8192
	ds_read_b128 v[12:15], v125 offset:8192
	s_waitcnt lgkmcnt(7)
	v_mfma_f32_16x16x32_bf16 v[98:101], v[98:101], v[18:21], 0
	s_waitcnt lgkmcnt(6)
	v_mfma_f32_16x16x32_bf16 v[98:101], v[102:105], v[22:25], v[98:101]
	s_waitcnt lgkmcnt(5)
	v_mfma_f32_16x16x32_bf16 v[98:101], v[106:109], v[26:29], v[98:101]
	s_waitcnt lgkmcnt(4)
	v_mfma_f32_16x16x32_bf16 v[118:121], v[110:113], v[30:33], v[98:101]
	s_nop 0
	ds_read_b128 v[126:129], v122 offset:12288
	ds_read_b128 v[130:133], v123 offset:12288
	ds_read_b128 v[134:137], v124 offset:12288
	ds_read_b128 v[138:141], v125 offset:12288
	s_waitcnt lgkmcnt(7)
	v_mfma_f32_16x16x32_bf16 v[0:3], v[0:3], v[18:21], 0
	s_waitcnt lgkmcnt(6)
	v_mfma_f32_16x16x32_bf16 v[0:3], v[4:7], v[22:25], v[0:3]
	s_waitcnt lgkmcnt(5)
	v_mfma_f32_16x16x32_bf16 v[0:3], v[8:11], v[26:29], v[0:3]
	s_waitcnt lgkmcnt(4)
	v_mfma_f32_16x16x32_bf16 v[122:125], v[12:15], v[30:33], v[0:3]
	s_nop 0
	s_nop 5
	v_add_u32_e32 v0, s58, v242
	v_add_u32_e32 v174, v0, v241
	ds_read_b128 v[98:101], v174 offset:16384
	ds_read_b128 v[102:105], v174 offset:18432
	ds_read_b128 v[106:109], v174 offset:20480
	ds_read_b128 v[110:113], v174 offset:22528
	s_waitcnt lgkmcnt(7)
	v_mfma_f32_16x16x32_bf16 v[0:3], v[126:129], v[18:21], 0
	s_waitcnt lgkmcnt(6)
	v_mfma_f32_16x16x32_bf16 v[0:3], v[130:133], v[22:25], v[0:3]
	s_waitcnt lgkmcnt(5)
	v_mfma_f32_16x16x32_bf16 v[0:3], v[134:137], v[26:29], v[0:3]
	s_waitcnt lgkmcnt(4)
	v_mfma_f32_16x16x32_bf16 v[126:129], v[138:141], v[30:33], v[0:3]
	s_nop 0
	s_mov_b64 s[48:49], -1
	s_cmp_lg_u32 s59, s2
	v_add_f32_e32 v176, 0x427af232, v173
	s_cbranch_scc0 .LBB0_823
	s_nop 1
	v_max3_f32 v0, v114, s41, v115
	v_max3_f32 v0, v0, v116, v117
	v_max3_f32 v0, v0, v118, v119
	v_max3_f32 v0, v0, v120, v121
	v_max3_f32 v0, v0, v122, v123
	v_max3_f32 v0, v0, v124, v125
	v_max3_f32 v0, v0, v126, v127
	v_max3_f32 v0, v0, v128, v129
	v_mov_b32_e32 v1, v0
	s_nop 1
	v_permlane16_swap_b32_e32 v0, v1
	v_max_f32_e32 v1, v1, v1
	v_max_f32_e32 v0, v0, v0
	v_max_f32_e32 v0, v0, v1
	v_mov_b32_e32 v1, v0
	s_nop 1
	v_permlane32_swap_b32_e32 v0, v1
	v_max_f32_e32 v1, v1, v1
	v_max_f32_e32 v0, v0, v0
	v_max_f32_e32 v0, v0, v1
	v_cndmask_b32_e64 v0, v231, v0, s[38:39]
	v_mov_b64_e32 v[160:161], v[68:69]
	v_mov_b64_e32 v[156:157], v[72:73]
	v_mov_b64_e32 v[152:153], v[76:77]
	v_mov_b64_e32 v[148:149], v[80:81]
	v_mov_b64_e32 v[144:145], v[84:85]
	v_mov_b64_e32 v[140:141], v[88:89]
	v_mov_b64_e32 v[136:137], v[92:93]
	v_mov_b64_e32 v[132:133], v[96:97]
	v_cmp_gt_f32_e32 vcc, v0, v176
	v_mov_b64_e32 v[158:159], v[66:67]
	v_mov_b64_e32 v[154:155], v[70:71]
	v_mov_b64_e32 v[150:151], v[74:75]
	v_mov_b64_e32 v[146:147], v[78:79]
	v_mov_b64_e32 v[142:143], v[82:83]
	v_mov_b64_e32 v[138:139], v[86:87]
	v_mov_b64_e32 v[134:135], v[90:91]
	v_mov_b64_e32 v[130:131], v[94:95]
	v_mov_b32_e32 v177, v170
	v_mov_b32_e32 v175, v173
	s_cbranch_vccz .LBB0_822
	v_max_f32_e32 v0, v0, v0
	v_max_f32_e32 v1, v173, v173
	v_max_f32_e32 v175, v1, v0
	v_sub_f32_e32 v0, v173, v175
	v_mul_f32_e32 v0, 0x3e0293ee, v0
	v_exp_f32_e32 v0, v0
	s_nop 0
	v_mul_f32_e32 v177, v170, v0
	v_pk_mul_f32 v[132:133], v[96:97], v[0:1] op_sel_hi:[1,0]
	v_pk_mul_f32 v[130:131], v[94:95], v[0:1] op_sel_hi:[1,0]
	v_pk_mul_f32 v[136:137], v[92:93], v[0:1] op_sel_hi:[1,0]
	v_pk_mul_f32 v[134:135], v[90:91], v[0:1] op_sel_hi:[1,0]
	v_pk_mul_f32 v[140:141], v[88:89], v[0:1] op_sel_hi:[1,0]
	v_pk_mul_f32 v[138:139], v[86:87], v[0:1] op_sel_hi:[1,0]
	v_pk_mul_f32 v[144:145], v[84:85], v[0:1] op_sel_hi:[1,0]
	v_pk_mul_f32 v[142:143], v[82:83], v[0:1] op_sel_hi:[1,0]
	v_pk_mul_f32 v[148:149], v[80:81], v[0:1] op_sel_hi:[1,0]
	v_pk_mul_f32 v[146:147], v[78:79], v[0:1] op_sel_hi:[1,0]
	v_pk_mul_f32 v[152:153], v[76:77], v[0:1] op_sel_hi:[1,0]
	v_pk_mul_f32 v[150:151], v[74:75], v[0:1] op_sel_hi:[1,0]
	v_pk_mul_f32 v[156:157], v[72:73], v[0:1] op_sel_hi:[1,0]
	v_pk_mul_f32 v[154:155], v[70:71], v[0:1] op_sel_hi:[1,0]
	v_pk_mul_f32 v[160:161], v[68:69], v[0:1] op_sel_hi:[1,0]
	v_pk_mul_f32 v[158:159], v[66:67], v[0:1] op_sel_hi:[1,0]

; DI unsigned pk2(float a, float b) { f32x2 v = {a, b}; bf16x2_t r = __builtin_convertvector(v, bf16x2_t); return __builtin_bit_cast(unsigned, r); }
; DI f32x4 mfma16(bf16x8 a, bf16x8 b, f32x4 c) { return __builtin_amdgcn_mfma_f32_16x16x32_bf16(a, b, c, 0, 0, 0); }
; #define SB0 __builtin_amdgcn_sched_barrier(0)
; DI void nsa_PV(f32x4 (&o)[8], const char* Vb, const bf16x8 (&pf)[2], bf16x8 (&v0)[4], int lr, int quad) {
;   bf16x8 v1[4], v2[4], v3[4];
;   SB0;
;   ldv4(v1, Vb, 1, lr, quad);
;   __builtin_amdgcn_s_setprio(1);
; #pragma unroll
;   for (int i = 0; i < 4; ++i) o[i] = mfma16(v0[i], pf[0], o[i]);
;   __builtin_amdgcn_s_setprio(0);
;   SB0;
;   ldv4(v2, Vb, 2, lr, quad);
;   __builtin_amdgcn_s_setprio(1);
; #pragma unroll
;   for (int i = 0; i < 4; ++i) o[4 + i] = mfma16(v1[i], pf[0], o[4 + i]);
;   __builtin_amdgcn_s_setprio(0);
;   SB0;
;   ldv4(v3, Vb, 3, lr, quad);
;   __builtin_amdgcn_s_setprio(1);
; #pragma unroll
;   for (int i = 0; i < 4; ++i) o[i] = mfma16(v2[i], pf[1], o[i]);
;   __builtin_amdgcn_s_setprio(0);
;   SB0;
;   __builtin_amdgcn_s_setprio(1);
; #pragma unroll
;   for (int i = 0; i < 4; ++i) o[4 + i] = mfma16(v3[i], pf[1], o[4 + i]);
;   __builtin_amdgcn_s_setprio(0);
; }
; DI void pack_p(const f32x4 (&s)[4], bf16x8 (&pf)[2]) {
; #pragma unroll
;   for (int s2 = 0; s2 < 2; ++s2)
;     pf[s2] = mk8(pk2(s[2 * s2][0], s[2 * s2][1]), pk2(s[2 * s2][2], s[2 * s2][3]),
;                  pk2(s[2 * s2 + 1][0], s[2 * s2 + 1][1]), pk2(s[2 * s2 + 1][2], s[2 * s2 + 1][3]));
; }
.LBB0_828:
	v_add_f32_e32 v170, v177, v178
	v_cvt_pk_bf16_f32 v0, v0, v1
	v_cvt_pk_bf16_f32 v1, v2, v3
	v_cvt_pk_bf16_f32 v2, v4, v5
	v_cvt_pk_bf16_f32 v3, v6, v7
	v_cvt_pk_bf16_f32 v4, v8, v9
	v_cvt_pk_bf16_f32 v5, v10, v11
	v_cvt_pk_bf16_f32 v6, v12, v13
	v_cvt_pk_bf16_f32 v7, v14, v15
	ds_read_b128 v[8:11], v174 offset:24576
	ds_read_b128 v[12:15], v174 offset:26624
	ds_read_b128 v[66:69], v174 offset:28672
	ds_read_b128 v[70:73], v174 offset:30720
	s_waitcnt lgkmcnt(4)
	v_mfma_f32_16x16x32_bf16 v[74:77], v[98:101], v[0:3], v[130:133]
	v_mfma_f32_16x16x32_bf16 v[78:81], v[102:105], v[0:3], v[134:137]
	v_mfma_f32_16x16x32_bf16 v[82:85], v[106:109], v[0:3], v[138:141]
	v_mfma_f32_16x16x32_bf16 v[98:101], v[110:113], v[0:3], v[142:145]
	s_nop 0
	v_add3_u32 v94, s58, v243, v241
	ds_read_b128 v[86:89], v94 offset:16384
	ds_read_b128 v[90:93], v94 offset:18432
	ds_read_b128 v[102:105], v94 offset:20480
	ds_read_b128 v[106:109], v94 offset:22528
	s_waitcnt lgkmcnt(5)
	v_mfma_f32_16x16x32_bf16 v[66:69], v[66:69], v[0:3], v[154:157]
	v_mfma_f32_16x16x32_bf16 v[8:11], v[8:11], v[0:3], v[146:149]
	v_mfma_f32_16x16x32_bf16 v[12:15], v[12:15], v[0:3], v[150:153]
	s_waitcnt lgkmcnt(4)
	v_mfma_f32_16x16x32_bf16 v[0:3], v[70:73], v[0:3], v[158:161]
	s_nop 0
	ds_read_b128 v[70:73], v94 offset:24576
	ds_read_b128 v[110:113], v94 offset:26624
	ds_read_b128 v[114:117], v94 offset:28672
	ds_read_b128 v[118:121], v94 offset:30720
	s_waitcnt lgkmcnt(7)
	v_mfma_f32_16x16x32_bf16 v[94:97], v[86:89], v[4:7], v[74:77]
	s_waitcnt lgkmcnt(6)
	v_mfma_f32_16x16x32_bf16 v[90:93], v[90:93], v[4:7], v[78:81]
	s_waitcnt lgkmcnt(5)
	v_mfma_f32_16x16x32_bf16 v[86:89], v[102:105], v[4:7], v[82:85]
	s_waitcnt lgkmcnt(4)
	v_mfma_f32_16x16x32_bf16 v[82:85], v[106:109], v[4:7], v[98:101]
	s_nop 0
	s_waitcnt lgkmcnt(3)
	v_mfma_f32_16x16x32_bf16 v[78:81], v[70:73], v[4:7], v[8:11]
	s_waitcnt lgkmcnt(2)
	v_mfma_f32_16x16x32_bf16 v[74:77], v[110:113], v[4:7], v[12:15]
	s_waitcnt lgkmcnt(1)
	v_mfma_f32_16x16x32_bf16 v[70:73], v[114:117], v[4:7], v[66:69]
	s_waitcnt lgkmcnt(0)
	v_mfma_f32_16x16x32_bf16 v[66:69], v[118:121], v[4:7], v[0:3]
	s_nop 0
	v_mov_b32_e32 v173, v175

; #define SB0 __builtin_amdgcn_sched_barrier(0)
; DI void nsa_S(f32x4 (&s)[4], const char* Kb, const char* Vb, const bf16x8 (&qf)[4], bf16x8 (&v0)[4], int lr, int quad) {
;   bf16x8 k0[4], k1[4], k2[4], k3[4];
;   ldk4(k0, Kb, 0, lr, quad); SB0;
;   ldk4(k1, Kb, 1, lr, quad); s[0] = mma4(k0, qf); SB0;
;   ldk4(k2, Kb, 2, lr, quad); s[1] = mma4(k1, qf); SB0;
;   ldk4(k3, Kb, 3, lr, quad); s[2] = mma4(k2, qf); SB0;
;   ldv4(v0, Vb, 0, lr, quad); s[3] = mma4(k3, qf); SB0;
; }
; DI void nsa_item(const Params& p, int b, int g, int qb, char* smem, int tid) {
;     ...
;       auto mf = [&](int kt, int i) __attribute__((always_inline)) {
;         int key = j * 64 + kt * 16 + quad * 4 + i;
;         return (key > qp) || (key <= qp - 512);
;       };
;       if (j * 64 + 63 <= q0 && j * 64 > q0 + 31 - 512) flash_update<false>(s, SCL, mx2, l2, o, mf, true);
;       else flash_update<true>(s, SCL, mx2, l2, o, mf, true);
.LBB0_844:
	s_lshl_b32 s5, s6, 15
	s_add_i32 s24, s23, s5
	v_add_u32_e32 v8, s24, v234
	v_add_u32_e32 v146, v8, v235
	v_add_u32_e32 v151, v8, v237
	v_add_u32_e32 v150, v8, v236
	ds_read_b128 v[0:3], v146
	ds_read_b128 v[4:7], v150
	v_add_u32_e32 v152, v8, v238
	ds_read_b128 v[8:11], v151
	ds_read_b128 v[12:15], v152
	ds_read_b128 v[130:133], v146 offset:4096
	ds_read_b128 v[134:137], v150 offset:4096
	ds_read_b128 v[138:141], v151 offset:4096
	ds_read_b128 v[142:145], v152 offset:4096
	s_waitcnt lgkmcnt(7)
	v_mfma_f32_16x16x32_bf16 v[0:3], v[0:3], v[18:21], 0
	s_waitcnt lgkmcnt(6)
	v_mfma_f32_16x16x32_bf16 v[0:3], v[4:7], v[22:25], v[0:3]
	s_waitcnt lgkmcnt(5)
	v_mfma_f32_16x16x32_bf16 v[0:3], v[8:11], v[26:29], v[0:3]
	s_waitcnt lgkmcnt(4)
	v_mfma_f32_16x16x32_bf16 v[158:161], v[12:15], v[30:33], v[0:3]
	s_nop 0
	s_nop 5
	ds_read_b128 v[0:3], v146 offset:8192
	ds_read_b128 v[4:7], v150 offset:8192
	ds_read_b128 v[8:11], v151 offset:8192
	ds_read_b128 v[12:15], v152 offset:8192
	s_waitcnt lgkmcnt(7)
	v_mfma_f32_16x16x32_bf16 v[130:133], v[130:133], v[18:21], 0
	s_waitcnt lgkmcnt(6)
	v_mfma_f32_16x16x32_bf16 v[130:133], v[134:137], v[22:25], v[130:133]
	s_waitcnt lgkmcnt(5)
	v_mfma_f32_16x16x32_bf16 v[130:133], v[138:141], v[26:29], v[130:133]
	s_waitcnt lgkmcnt(4)
	v_mfma_f32_16x16x32_bf16 v[154:157], v[142:145], v[30:33], v[130:133]
	s_nop 0
	ds_read_b128 v[146:149], v146 offset:12288
	ds_read_b128 v[162:165], v150 offset:12288
	ds_read_b128 v[166:169], v151 offset:12288
	ds_read_b128 v[170:173], v152 offset:12288
	s_waitcnt lgkmcnt(7)
	v_mfma_f32_16x16x32_bf16 v[0:3], v[0:3], v[18:21], 0
	s_waitcnt lgkmcnt(6)
	v_mfma_f32_16x16x32_bf16 v[0:3], v[4:7], v[22:25], v[0:3]
	s_waitcnt lgkmcnt(5)
	v_mfma_f32_16x16x32_bf16 v[0:3], v[8:11], v[26:29], v[0:3]
	s_waitcnt lgkmcnt(4)
	v_mfma_f32_16x16x32_bf16 v[150:153], v[12:15], v[30:33], v[0:3]
	s_nop 0
	s_nop 5
	v_add_u32_e32 v0, s24, v242
	v_add_u32_e32 v247, v0, v241
	ds_read_b128 v[130:133], v247 offset:16384
	ds_read_b128 v[134:137], v247 offset:18432
	ds_read_b128 v[138:141], v247 offset:20480
	ds_read_b128 v[142:145], v247 offset:22528
	s_waitcnt lgkmcnt(7)
	v_mfma_f32_16x16x32_bf16 v[0:3], v[146:149], v[18:21], 0
	s_waitcnt lgkmcnt(6)
	v_mfma_f32_16x16x32_bf16 v[0:3], v[162:165], v[22:25], v[0:3]
	s_waitcnt lgkmcnt(5)
	v_mfma_f32_16x16x32_bf16 v[0:3], v[166:169], v[26:29], v[0:3]
	s_waitcnt lgkmcnt(4)
	v_mfma_f32_16x16x32_bf16 v[146:149], v[170:173], v[30:33], v[0:3]
	s_nop 0
	s_lshl_b32 s6, s4, 6
	s_or_b32 s4, s6, 63
	s_cmp_le_u32 s4, s85
	s_cselect_b64 s[4:5], -1, 0
	s_cmp_gt_i32 s6, s21
	s_cselect_b64 s[8:9], -1, 0
	s_and_b64 s[8:9], s[4:5], s[8:9]
	s_mov_b64 s[4:5], -1
	s_andn2_b64 vcc, exec, s[8:9]
	v_add_f32_e32 v249, 0x427af232, v246
	s_cbranch_vccz .LBB0_849
; DI float ex2(float x) { return __builtin_amdgcn_exp2f(x); }
; template <bool MASKED, class MF>
; DI void flash_update(f32x4 (&s)[4], float scl, float& mx, float& ls, f32x4 (&o)[8], MF maskfn, bool lane_on) {
;   float tmax = -1e30f;
; #pragma unroll
;   for (int kt = 0; kt < 4; ++kt)
; #pragma unroll
;     for (int i = 0; i < 4; ++i) {
;       if (MASKED) { if (maskfn(kt, i)) s[kt][i] = -1e30f; }
;       tmax = fmaxf(tmax, s[kt][i]);
;     }
;   tmax = rowmax4(tmax);
;   if (!lane_on) tmax = -1e30f;
;   const float th = 8.f / scl;
;   if (__any(tmax > mx + th)) {
;     const float mnew = fmaxf(mx, tmax);
;     const float alpha = ex2((mx - mnew) * scl);
;     ls *= alpha;
; #pragma unroll
;     for (int dt = 0; dt < 8; ++dt) o[dt] *= alpha;
;     mx = mnew;
;   }
	v_or_b32_e32 v15, s6, v214
	v_cmp_gt_i32_e32 vcc, v15, v233
	v_cmp_le_i32_e64 s[4:5], v15, v245
	s_or_b64 vcc, vcc, s[4:5]
	v_cndmask_b32_e32 v0, v158, v231, vcc
	v_cmp_ge_i32_e32 vcc, v15, v233
	v_cmp_lt_i32_e64 s[4:5], v15, v245
	s_or_b64 vcc, vcc, s[4:5]
	v_or_b32_e32 v2, 2, v15
	v_cndmask_b32_e32 v1, v159, v231, vcc
	v_cmp_gt_i32_e32 vcc, v2, v233
	v_cmp_le_i32_e64 s[4:5], v2, v245
	s_or_b64 vcc, vcc, s[4:5]
	v_or_b32_e32 v3, 3, v15
	v_cndmask_b32_e32 v2, v160, v231, vcc
	v_cmp_gt_i32_e32 vcc, v3, v233
	v_cmp_le_i32_e64 s[4:5], v3, v245
	s_or_b64 s[4:5], vcc, s[4:5]
	v_max3_f32 v4, v0, s41, v1
	v_cndmask_b32_e64 v3, v161, v231, s[4:5]
	v_max3_f32 v6, v4, v2, v3
	v_or_b32_e32 v4, 16, v15
	v_cmp_gt_i32_e32 vcc, v4, v233
	v_cmp_le_i32_e64 s[6:7], v4, v245
	s_or_b64 vcc, vcc, s[6:7]
	v_or_b32_e32 v5, 17, v15
	v_cndmask_b32_e32 v4, v154, v231, vcc
	v_cmp_gt_i32_e32 vcc, v5, v233
	v_cmp_le_i32_e64 s[6:7], v5, v245
	s_or_b64 vcc, vcc, s[6:7]
	v_cndmask_b32_e32 v5, v155, v231, vcc
	v_max3_f32 v8, v6, v4, v5
	v_or_b32_e32 v6, 18, v15
	v_cmp_gt_i32_e32 vcc, v6, v233
	v_cmp_le_i32_e64 s[6:7], v6, v245
	s_or_b64 vcc, vcc, s[6:7]
	v_or_b32_e32 v7, 19, v15
	v_cndmask_b32_e32 v6, v156, v231, vcc
	v_cmp_gt_i32_e32 vcc, v7, v233
	v_cmp_le_i32_e64 s[6:7], v7, v245
	s_or_b64 s[6:7], vcc, s[6:7]
	v_or_b32_e32 v9, 33, v15
	v_cndmask_b32_e64 v7, v157, v231, s[6:7]
	v_max3_f32 v10, v8, v6, v7
	v_or_b32_e32 v8, 32, v15
	v_cmp_gt_i32_e32 vcc, v8, v233
	v_cmp_le_i32_e64 s[8:9], v8, v245
	s_or_b64 vcc, vcc, s[8:9]
	v_cndmask_b32_e32 v8, v150, v231, vcc
	v_cmp_gt_i32_e32 vcc, v9, v233
	v_cmp_le_i32_e64 s[8:9], v9, v245
	s_or_b64 vcc, vcc, s[8:9]
	v_cndmask_b32_e32 v9, v151, v231, vcc
	v_max3_f32 v12, v10, v8, v9
	v_or_b32_e32 v10, 34, v15
	v_cmp_gt_i32_e32 vcc, v10, v233
	v_cmp_le_i32_e64 s[8:9], v10, v245
	s_or_b64 vcc, vcc, s[8:9]
	v_or_b32_e32 v11, 35, v15
	v_cndmask_b32_e32 v10, v152, v231, vcc
	v_cmp_gt_i32_e32 vcc, v11, v233
	v_cmp_le_i32_e64 s[8:9], v11, v245
	s_or_b64 s[8:9], vcc, s[8:9]
	v_or_b32_e32 v13, 49, v15
	v_cndmask_b32_e64 v11, v153, v231, s[8:9]
	v_max3_f32 v14, v12, v10, v11
	v_or_b32_e32 v12, 48, v15
	v_cmp_gt_i32_e32 vcc, v12, v233
	v_cmp_le_i32_e64 s[10:11], v12, v245
	s_or_b64 vcc, vcc, s[10:11]
	v_cndmask_b32_e32 v12, v146, v231, vcc
	v_cmp_gt_i32_e32 vcc, v13, v233
	v_cmp_le_i32_e64 s[10:11], v13, v245
	s_or_b64 vcc, vcc, s[10:11]
	v_cndmask_b32_e32 v13, v147, v231, vcc
	v_max3_f32 v162, v14, v12, v13
	v_or_b32_e32 v14, 50, v15
	v_cmp_gt_i32_e32 vcc, v14, v233
	v_cmp_le_i32_e64 s[10:11], v14, v245
	s_or_b64 vcc, vcc, s[10:11]
	v_or_b32_e32 v15, 51, v15
	v_cndmask_b32_e32 v14, v148, v231, vcc
	v_cmp_gt_i32_e32 vcc, v15, v233
	v_cmp_le_i32_e64 s[10:11], v15, v245
	s_or_b64 s[10:11], vcc, s[10:11]
	s_nop 0
	v_cndmask_b32_e64 v15, v149, v231, s[10:11]
	v_max3_f32 v162, v162, v14, v15
	v_mov_b32_e32 v163, v162
	s_nop 1
	v_permlane16_swap_b32_e32 v162, v163
	v_max_f32_e32 v163, v163, v163
	v_max_f32_e32 v162, v162, v162
	v_max_f32_e32 v162, v162, v163
	v_mov_b32_e32 v163, v162
	s_nop 1
	v_permlane32_swap_b32_e32 v162, v163
	v_max_f32_e32 v163, v163, v163
	v_max_f32_e32 v162, v162, v162
	v_max_f32_e32 v162, v162, v163
	v_cmp_gt_f32_e32 vcc, v162, v249
	s_cbranch_vccz .LBB0_847
	v_max_f32_e32 v7, v162, v162
	v_max_f32_e32 v11, v246, v246
	v_max_f32_e32 v248, v11, v7
	v_sub_f32_e32 v7, v246, v248
	v_mul_f32_e32 v7, 0x3e0293ee, v7
	v_exp_f32_e32 v190, v7
	v_cndmask_b32_e64 v3, v161, v231, s[4:5]
	v_cndmask_b32_e64 v7, v157, v231, s[6:7]
	v_cndmask_b32_e64 v11, v153, v231, s[8:9]
	v_cndmask_b32_e64 v15, v149, v231, s[10:11]
	v_mul_f32_e32 v250, v244, v190
	v_pk_mul_f32 v[164:165], v[128:129], v[190:191] op_sel_hi:[1,0]
	v_pk_mul_f32 v[162:163], v[126:127], v[190:191] op_sel_hi:[1,0]
	v_pk_mul_f32 v[168:169], v[124:125], v[190:191] op_sel_hi:[1,0]
	v_pk_mul_f32 v[166:167], v[122:123], v[190:191] op_sel_hi:[1,0]
	v_pk_mul_f32 v[172:173], v[120:121], v[190:191] op_sel_hi:[1,0]
	v_pk_mul_f32 v[170:171], v[118:119], v[190:191] op_sel_hi:[1,0]
	v_pk_mul_f32 v[176:177], v[116:117], v[190:191] op_sel_hi:[1,0]
	v_pk_mul_f32 v[174:175], v[114:115], v[190:191] op_sel_hi:[1,0]
	v_pk_mul_f32 v[180:181], v[112:113], v[190:191] op_sel_hi:[1,0]
	v_pk_mul_f32 v[178:179], v[110:111], v[190:191] op_sel_hi:[1,0]
	v_pk_mul_f32 v[184:185], v[108:109], v[190:191] op_sel_hi:[1,0]
	v_pk_mul_f32 v[182:183], v[106:107], v[190:191] op_sel_hi:[1,0]
	v_pk_mul_f32 v[188:189], v[104:105], v[190:191] op_sel_hi:[1,0]
	v_pk_mul_f32 v[186:187], v[102:103], v[190:191] op_sel_hi:[1,0]
	v_pk_mul_f32 v[192:193], v[100:101], v[190:191] op_sel_hi:[1,0]
	v_pk_mul_f32 v[190:191], v[98:99], v[190:191] op_sel_hi:[1,0]
	s_branch .LBB0_848

; DI unsigned pk2(float a, float b) { f32x2 v = {a, b}; bf16x2_t r = __builtin_convertvector(v, bf16x2_t); return __builtin_bit_cast(unsigned, r); }
; DI f32x4 mfma16(bf16x8 a, bf16x8 b, f32x4 c) { return __builtin_amdgcn_mfma_f32_16x16x32_bf16(a, b, c, 0, 0, 0); }
; #define SB0 __builtin_amdgcn_sched_barrier(0)
; DI void nsa_PV(f32x4 (&o)[8], const char* Vb, const bf16x8 (&pf)[2], bf16x8 (&v0)[4], int lr, int quad) {
;   bf16x8 v1[4], v2[4], v3[4];
;   SB0;
;   ldv4(v1, Vb, 1, lr, quad);
;   __builtin_amdgcn_s_setprio(1);
; #pragma unroll
;   for (int i = 0; i < 4; ++i) o[i] = mfma16(v0[i], pf[0], o[i]);
;   __builtin_amdgcn_s_setprio(0);
;   SB0;
;   ldv4(v2, Vb, 2, lr, quad);
;   __builtin_amdgcn_s_setprio(1);
; #pragma unroll
;   for (int i = 0; i < 4; ++i) o[4 + i] = mfma16(v1[i], pf[0], o[4 + i]);
;   __builtin_amdgcn_s_setprio(0);
;   SB0;
;   ldv4(v3, Vb, 3, lr, quad);
;   __builtin_amdgcn_s_setprio(1);
; #pragma unroll
;   for (int i = 0; i < 4; ++i) o[i] = mfma16(v2[i], pf[1], o[i]);
;   __builtin_amdgcn_s_setprio(0);
;   SB0;
;   __builtin_amdgcn_s_setprio(1);
; #pragma unroll
;   for (int i = 0; i < 4; ++i) o[4 + i] = mfma16(v3[i], pf[1], o[4 + i]);
;   __builtin_amdgcn_s_setprio(0);
; }
; DI void pack_p(const f32x4 (&s)[4], bf16x8 (&pf)[2]) {
; #pragma unroll
;   for (int s2 = 0; s2 < 2; ++s2)
;     pf[s2] = mk8(pk2(s[2 * s2][0], s[2 * s2][1]), pk2(s[2 * s2][2], s[2 * s2][3]),
;                  pk2(s[2 * s2 + 1][0], s[2 * s2 + 1][1]), pk2(s[2 * s2 + 1][2], s[2 * s2 + 1][3]));
; }
.LBB0_853:
	s_xor_b64 s[4:5], s[14:15], -1
	v_add_f32_e32 v244, v250, v251
	v_cvt_pk_bf16_f32 v0, v0, v1
	v_cvt_pk_bf16_f32 v1, v2, v3
	v_cvt_pk_bf16_f32 v2, v4, v5
	v_cvt_pk_bf16_f32 v3, v6, v7
	v_cvt_pk_bf16_f32 v4, v8, v9
	v_cvt_pk_bf16_f32 v5, v10, v11
	v_cvt_pk_bf16_f32 v6, v12, v13
	v_cvt_pk_bf16_f32 v7, v14, v15
	ds_read_b128 v[8:11], v247 offset:24576
	ds_read_b128 v[12:15], v247 offset:26624
	ds_read_b128 v[98:101], v247 offset:28672
	ds_read_b128 v[102:105], v247 offset:30720
	s_waitcnt lgkmcnt(4)
	v_mfma_f32_16x16x32_bf16 v[106:109], v[130:133], v[0:3], v[162:165]
	v_mfma_f32_16x16x32_bf16 v[110:113], v[134:137], v[0:3], v[166:169]
	v_mfma_f32_16x16x32_bf16 v[114:117], v[138:141], v[0:3], v[170:173]
	v_mfma_f32_16x16x32_bf16 v[130:133], v[142:145], v[0:3], v[174:177]
	s_nop 0
	v_add3_u32 v126, s24, v243, v241
	ds_read_b128 v[118:121], v126 offset:16384
	ds_read_b128 v[122:125], v126 offset:18432
	ds_read_b128 v[134:137], v126 offset:20480
	ds_read_b128 v[138:141], v126 offset:22528
	s_waitcnt lgkmcnt(5)
	v_mfma_f32_16x16x32_bf16 v[98:101], v[98:101], v[0:3], v[186:189]
	v_mfma_f32_16x16x32_bf16 v[8:11], v[8:11], v[0:3], v[178:181]
	v_mfma_f32_16x16x32_bf16 v[12:15], v[12:15], v[0:3], v[182:185]
	s_waitcnt lgkmcnt(4)
	v_mfma_f32_16x16x32_bf16 v[0:3], v[102:105], v[0:3], v[190:193]
	s_nop 0
	ds_read_b128 v[102:105], v126 offset:24576
	ds_read_b128 v[142:145], v126 offset:26624
	ds_read_b128 v[146:149], v126 offset:28672
	ds_read_b128 v[150:153], v126 offset:30720
	s_waitcnt lgkmcnt(7)
	v_mfma_f32_16x16x32_bf16 v[126:129], v[118:121], v[4:7], v[106:109]
	s_waitcnt lgkmcnt(6)
	v_mfma_f32_16x16x32_bf16 v[122:125], v[122:125], v[4:7], v[110:113]
	s_waitcnt lgkmcnt(5)
	v_mfma_f32_16x16x32_bf16 v[118:121], v[134:137], v[4:7], v[114:117]
	s_waitcnt lgkmcnt(4)
	v_mfma_f32_16x16x32_bf16 v[114:117], v[138:141], v[4:7], v[130:133]
	s_nop 0
	s_waitcnt lgkmcnt(3)
	v_mfma_f32_16x16x32_bf16 v[110:113], v[102:105], v[4:7], v[8:11]
	s_waitcnt lgkmcnt(2)
	v_mfma_f32_16x16x32_bf16 v[106:109], v[142:145], v[4:7], v[12:15]
	s_waitcnt lgkmcnt(1)
	v_mfma_f32_16x16x32_bf16 v[102:105], v[146:149], v[4:7], v[98:101]
	s_waitcnt lgkmcnt(0)
	v_mfma_f32_16x16x32_bf16 v[98:101], v[150:153], v[4:7], v[0:3]
	s_nop 0
	s_mov_b32 s6, 1
	s_mov_b64 s[14:15], 0
	s_and_b64 vcc, exec, s[4:5]
	s_cbranch_vccnz .LBB0_855
